# attention PV: counted lgkmcnt(6) per MFMA instead of a full LDS drain before each 4-MFMA group (reads stay in flight)
# speedup vs baseline: 1.0161x; 1.0115x over previous
; #define LAS __attribute__((address_space(3)))
; #define SBAR() __builtin_amdgcn_sched_barrier(0)
; __device__ __forceinline__ void qkt(f32x16& p0, f32x16& p1, const LAS char* Ks, const bf16x8* qr, const f32x16& negm, int r32, int hi) {
; #pragma unroll
;     for (int d0 = 0; d0 < 4; ++d0) { const int cb = (d0 * 16 + hi * 8) * 2;
;         const bf16x8 b0 = *(const LAS bf16x8*)(Ks + KSWZ(r32, cb));
;         const bf16x8 b1 = *(const LAS bf16x8*)(Ks + KSWZ(32 + r32, cb));
;         if (d0 == 0) { p0 = __builtin_amdgcn_mfma_f32_32x32x16_bf16(b0, qr[0], negm, 0, 0, 0); p1 = __builtin_amdgcn_mfma_f32_32x32x16_bf16(b1, qr[0], negm, 0, 0, 0); }
;         else { p0 = __builtin_amdgcn_mfma_f32_32x32x16_bf16(b0, qr[d0], p0, 0, 0, 0); p1 = __builtin_amdgcn_mfma_f32_32x32x16_bf16(b1, qr[d0], p1, 0, 0, 0); } }
; }
; __device__ __forceinline__ int v_st(int k, int c) { const int kk = (k & ~0xC) | ((k & 4) << 1) | ((k & 8) >> 1); return ((kk >> 3) * 4 + (c >> 5)) * 512 + ((kk & 7) * 32 + (c & 31)) * 2; }
; __device__ __forceinline__ int v_rd_base(int lane) { return ((lane & 3) << 3) | (((lane >> 2) & 3) << 6) | (((lane >> 4) & 1) << 5) | (((lane >> 5) & 1) << 8); }
; template <int OFF> __device__ __forceinline__ s16x4 tr_read(int vb) {
;     s16x4 r; asm volatile("ds_read_b64_tr_b16 %0, %1 offset:%2" : "=&v"(r) : "v"(vb), "i"(OFF) : "memory"); return r;
; }
; template <int D0> __device__ __forceinline__ void pv_one(f32x16& od, int vb, bf16x8 pa0, bf16x8 pa1, bf16x8 pa2, bf16x8 pa3) {
;     const s16x4 l0 = tr_read<v_rd_off(D0, 0, 0)>(vb), h0 = tr_read<v_rd_off(D0, 0, 1)>(vb), l1 = tr_read<v_rd_off(D0, 1, 0)>(vb), h1 = tr_read<v_rd_off(D0, 1, 1)>(vb);
;     const s16x4 l2 = tr_read<v_rd_off(D0, 2, 0)>(vb), h2 = tr_read<v_rd_off(D0, 2, 1)>(vb), l3 = tr_read<v_rd_off(D0, 3, 0)>(vb), h3 = tr_read<v_rd_off(D0, 3, 1)>(vb);
;     asm volatile("s_waitcnt lgkmcnt(0)" ::: "memory"); SBAR();
;     ...
;     od = __builtin_amdgcn_mfma_f32_32x32x16_bf16(pa0, PK(l0, h0), od, 0, 0, 0);
;     od = __builtin_amdgcn_mfma_f32_32x32x16_bf16(pa1, PK(l1, h1), od, 0, 0, 0);
;     od = __builtin_amdgcn_mfma_f32_32x32x16_bf16(pa2, PK(l2, h2), od, 0, 0, 0);
;     od = __builtin_amdgcn_mfma_f32_32x32x16_bf16(pa3, PK(l3, h3), od, 0, 0, 0);
;     ...
; }
; __device__ __forceinline__ void pv_d0(f32x16* o, int vb, bf16x8 pa0, bf16x8 pa1, bf16x8 pa2, bf16x8 pa3) {
.LBB0_591:
	s_add_i32 s2, s48, -4
	s_setprio 1
	s_and_b32 s61, s2, 3
	v_lshl_add_u32 v0, s61, 13, v241
	v_add_u32_e32 v6, v0, v237
	ds_read_b128 v[2:5], v6 offset:4096
	ds_read_b128 v[6:9], v6
	s_and_b32 s2, s39, 0xc000
	s_waitcnt lgkmcnt(1)
	v_mfma_f32_32x32x16_bf16 v[112:127], v[2:5], v[156:159], v[96:111]
	s_waitcnt lgkmcnt(0)
	v_mfma_f32_32x32x16_bf16 v[128:143], v[6:9], v[156:159], v[96:111]
	v_add_u32_e32 v6, v0, v238
	ds_read_b128 v[2:5], v6 offset:4096
	ds_read_b128 v[6:9], v6
	s_waitcnt lgkmcnt(1)
	v_mfma_f32_32x32x16_bf16 v[112:127], v[2:5], v[152:155], v[112:127]
	s_waitcnt lgkmcnt(0)
	v_mfma_f32_32x32x16_bf16 v[128:143], v[6:9], v[152:155], v[128:143]
	v_add_u32_e32 v6, v0, v239
	ds_read_b128 v[2:5], v6 offset:4096
	ds_read_b128 v[6:9], v6
	v_add_u32_e32 v0, v0, v240
	s_waitcnt lgkmcnt(1)
	v_mfma_f32_32x32x16_bf16 v[112:127], v[2:5], v[148:151], v[112:127]
	s_waitcnt lgkmcnt(0)
	v_mfma_f32_32x32x16_bf16 v[128:143], v[6:9], v[148:151], v[128:143]
	ds_read_b128 v[2:5], v0 offset:4096
	ds_read_b128 v[6:9], v0
	v_add_u32_e32 v0, s2, v242
	s_waitcnt lgkmcnt(1)
	v_mfma_f32_32x32x16_bf16 v[112:127], v[2:5], v[144:147], v[112:127]
	ds_read_b64_tr_b16 v[2:3], v0 offset:0
	ds_read_b64_tr_b16 v[4:5], v0 offset:0x800
	s_waitcnt lgkmcnt(0)
	v_mfma_f32_32x32x16_bf16 v[128:143], v[6:9], v[144:147], v[128:143]
	ds_read_b64_tr_b16 v[6:7], v0 offset:0x1000
	ds_read_b64_tr_b16 v[8:9], v0 offset:0x1800
	ds_read_b64_tr_b16 v[10:11], v0 offset:0x2000
	ds_read_b64_tr_b16 v[12:13], v0 offset:0x2800
	ds_read_b64_tr_b16 v[80:81], v0 offset:0x3000
	ds_read_b64_tr_b16 v[82:83], v0 offset:0x3800
	s_waitcnt lgkmcnt(6)
	v_mfma_f32_32x32x16_bf16 v[64:79], v[184:187], v[2:5], v[64:79]
	ds_read_b64_tr_b16 v[2:3], v0 offset:0x200
	ds_read_b64_tr_b16 v[4:5], v0 offset:0xa00
	s_waitcnt lgkmcnt(6)
	v_mfma_f32_32x32x16_bf16 v[64:79], v[188:191], v[6:9], v[64:79]
	ds_read_b64_tr_b16 v[6:7], v0 offset:0x1200
	ds_read_b64_tr_b16 v[8:9], v0 offset:0x1a00
	s_waitcnt lgkmcnt(6)
	v_mfma_f32_32x32x16_bf16 v[64:79], v[192:195], v[10:13], v[64:79]
	ds_read_b64_tr_b16 v[10:11], v0 offset:0x2200
	ds_read_b64_tr_b16 v[12:13], v0 offset:0x2a00
	s_waitcnt lgkmcnt(6)
	v_mfma_f32_32x32x16_bf16 v[64:79], v[196:199], v[80:83], v[64:79]
	ds_read_b64_tr_b16 v[80:81], v0 offset:0x3200
	ds_read_b64_tr_b16 v[82:83], v0 offset:0x3a00
	s_waitcnt lgkmcnt(6)
	v_mfma_f32_32x32x16_bf16 v[48:63], v[184:187], v[2:5], v[48:63]
	ds_read_b64_tr_b16 v[2:3], v0 offset:0x400
	ds_read_b64_tr_b16 v[4:5], v0 offset:0xc00
	s_waitcnt lgkmcnt(6)
	v_mfma_f32_32x32x16_bf16 v[48:63], v[188:191], v[6:9], v[48:63]
	ds_read_b64_tr_b16 v[6:7], v0 offset:0x1400
	ds_read_b64_tr_b16 v[8:9], v0 offset:0x1c00
	s_waitcnt lgkmcnt(6)
	v_mfma_f32_32x32x16_bf16 v[48:63], v[192:195], v[10:13], v[48:63]
	ds_read_b64_tr_b16 v[10:11], v0 offset:0x2400
	ds_read_b64_tr_b16 v[12:13], v0 offset:0x2c00
	s_waitcnt lgkmcnt(6)
	v_mfma_f32_32x32x16_bf16 v[48:63], v[196:199], v[80:83], v[48:63]
	ds_read_b64_tr_b16 v[80:81], v0 offset:0x3400
	ds_read_b64_tr_b16 v[82:83], v0 offset:0x3c00
	s_waitcnt lgkmcnt(6)
	v_mfma_f32_32x32x16_bf16 v[32:47], v[184:187], v[2:5], v[32:47]
	ds_read_b64_tr_b16 v[2:3], v0 offset:0x600
	ds_read_b64_tr_b16 v[4:5], v0 offset:0xe00
	s_waitcnt lgkmcnt(6)
	v_mfma_f32_32x32x16_bf16 v[32:47], v[188:191], v[6:9], v[32:47]
	ds_read_b64_tr_b16 v[6:7], v0 offset:0x1600
	ds_read_b64_tr_b16 v[8:9], v0 offset:0x1e00
	s_waitcnt lgkmcnt(6)
	v_mfma_f32_32x32x16_bf16 v[32:47], v[192:195], v[10:13], v[32:47]
	ds_read_b64_tr_b16 v[10:11], v0 offset:0x2600
	ds_read_b64_tr_b16 v[12:13], v0 offset:0x2e00
	s_waitcnt lgkmcnt(6)
	v_mfma_f32_32x32x16_bf16 v[32:47], v[196:199], v[80:83], v[32:47]
	ds_read_b64_tr_b16 v[80:81], v0 offset:0x3600
	ds_read_b64_tr_b16 v[82:83], v0 offset:0x3e00
	s_waitcnt lgkmcnt(6)
	v_mfma_f32_32x32x16_bf16 v[16:31], v[184:187], v[2:5], v[16:31]
	s_waitcnt lgkmcnt(4)
	v_mfma_f32_32x32x16_bf16 v[16:31], v[188:191], v[6:9], v[16:31]
	s_waitcnt lgkmcnt(2)
	v_mfma_f32_32x32x16_bf16 v[16:31], v[192:195], v[10:13], v[16:31]
	s_waitcnt lgkmcnt(0)
	v_mfma_f32_32x32x16_bf16 v[16:31], v[196:199], v[80:83], v[16:31]
	s_setprio 0
	s_add_i32 s2, s48, -2
	s_and_b32 s2, s2, 3
	s_lshl_b32 s3, s2, 14
	s_add_i32 s3, s3, 0
	s_waitcnt lgkmcnt(0)
	s_barrier
	v_add_u32_e32 v0, s3, v233
	s_add_i32 s49, s48, -1
	s_waitcnt vmcnt(2)
	ds_write_b128 v0, v[172:175]
	v_add_u32_e32 v0, s3, v234
	s_cmp_lt_u32 s49, s45
	s_waitcnt vmcnt(1)
	ds_write_b128 v0, v[176:179]
	v_lshl_add_u32 v0, s2, 13, v235
	s_cselect_b64 s[2:3], -1, 0
	s_cmp_ge_u32 s49, s45
	v_lshl_add_u64 v[188:189], v[218:219], 0, s[36:37]
	v_lshl_add_u64 v[14:15], v[216:217], 0, s[36:37]
	s_waitcnt vmcnt(0)
	ds_write_b128 v0, v[180:183]
	s_cbranch_scc1 .LBB0_593
	v_add_co_u32_e32 v2, vcc, 0xef40000, v188
	s_nop 1
	v_addc_co_u32_e32 v3, vcc, 0, v189, vcc
	v_add_co_u32_e32 v4, vcc, 0xef48000, v188
	s_nop 1
	v_addc_co_u32_e32 v5, vcc, 0, v189, vcc
	global_load_dwordx4 v[160:163], v[2:3], off
	global_load_dwordx4 v[164:167], v[4:5], off
	v_add_co_u32_e32 v2, vcc, 0xcf40000, v14
	s_nop 1
	v_addc_co_u32_e32 v3, vcc, 0, v15, vcc
	global_load_dwordx4 v[168:171], v[2:3], off

; __device__ __forceinline__ void partialSM(f32x16& p0, f32x16& p1, float& mhat, f32x16& negm, float& alpha, const bool first) {
;     ...
;     for (int r = 0; r < 16; ++r) p0[r] = __builtin_amdgcn_exp2f(p0[r]);
; }
; __device__ __forceinline__ void finishSM(f32x16& p0, f32x16& p1, float alpha, float& l_reg, bf16x8& pa0, bf16x8& pa1, bf16x8& pa2, bf16x8& pa3) {
; #pragma unroll
;     for (int r = 0; r < 16; ++r) p1[r] = __builtin_amdgcn_exp2f(p1[r]);
;     float ps = 0;
; #pragma unroll
;     for (int r = 0; r < 16; ++r) ps += p0[r];
; #pragma unroll
;     for (int r = 0; r < 16; ++r) ps += p1[r];
;     { auto rr = __builtin_amdgcn_permlane32_swap(__float_as_uint(ps), __float_as_uint(ps), false, false);
;       ps = __uint_as_float(rr[0]) + __uint_as_float(rr[1]); }
;     l_reg = l_reg * alpha + ps;
.LBB0_598:
	v_exp_f32_e32 v2, v128
	v_exp_f32_e32 v3, v129
	v_exp_f32_e32 v4, v130
	v_exp_f32_e32 v5, v131
	v_exp_f32_e32 v6, v132
	v_add_f32_e32 v132, 0, v2
	v_exp_f32_e32 v7, v133
	v_add_f32_e32 v132, v3, v132
	v_exp_f32_e32 v8, v134
	v_add_f32_e32 v132, v4, v132
	v_exp_f32_e32 v9, v135
	v_add_f32_e32 v132, v5, v132
	v_exp_f32_e32 v10, v136
	v_add_f32_e32 v132, v6, v132
	v_exp_f32_e32 v11, v137
	v_add_f32_e32 v132, v7, v132
	v_exp_f32_e32 v12, v138
	v_add_f32_e32 v132, v8, v132
	v_exp_f32_e32 v13, v139
	v_add_f32_e32 v132, v9, v132
	v_exp_f32_e32 v128, v140
	v_add_f32_e32 v132, v10, v132
	v_exp_f32_e32 v129, v141
	v_add_f32_e32 v132, v11, v132
	v_exp_f32_e32 v130, v142
	v_add_f32_e32 v132, v12, v132
	v_exp_f32_e32 v131, v143
	v_add_f32_e32 v132, v13, v132
	v_exp_f32_e32 v112, v112
	v_add_f32_e32 v132, v128, v132
	v_exp_f32_e32 v113, v113
	v_add_f32_e32 v132, v129, v132
	v_exp_f32_e32 v114, v114
	v_add_f32_e32 v132, v130, v132
	v_exp_f32_e32 v115, v115
	v_add_f32_e32 v132, v131, v132
	v_exp_f32_e32 v116, v116
	v_add_f32_e32 v132, v112, v132
	v_exp_f32_e32 v117, v117
	v_add_f32_e32 v132, v113, v132
	v_exp_f32_e32 v118, v118
	v_add_f32_e32 v132, v114, v132
	v_exp_f32_e32 v119, v119
	v_add_f32_e32 v132, v115, v132
	v_exp_f32_e32 v120, v120
	v_add_f32_e32 v132, v116, v132
	v_exp_f32_e32 v121, v121
	v_add_f32_e32 v132, v117, v132
	v_exp_f32_e32 v122, v122
	v_add_f32_e32 v132, v118, v132
	v_exp_f32_e32 v123, v123
	v_add_f32_e32 v132, v119, v132
	v_exp_f32_e32 v124, v124
	v_add_f32_e32 v132, v120, v132
	v_exp_f32_e32 v125, v125
	v_add_f32_e32 v132, v121, v132
	v_exp_f32_e32 v126, v126
	v_add_f32_e32 v132, v122, v132
	v_exp_f32_e32 v127, v127
	v_add_f32_e32 v132, v123, v132
	v_add_f32_e32 v132, v124, v132
	v_add_f32_e32 v132, v125, v132
	v_add_f32_e32 v132, v126, v132
	v_add_f32_e32 v190, v127, v132
	s_waitcnt lgkmcnt(0)
	s_barrier
; #define LAS __attribute__((address_space(3)))
; __device__ __forceinline__ void finishSM(f32x16& p0, f32x16& p1, float alpha, float& l_reg, bf16x8& pa0, bf16x8& pa1, bf16x8& pa2, bf16x8& pa3) {
; #pragma unroll
;     for (int r = 0; r < 16; ++r) p1[r] = __builtin_amdgcn_exp2f(p1[r]);
;     float ps = 0;
; #pragma unroll
;     for (int r = 0; r < 16; ++r) ps += p0[r];
; #pragma unroll
;     for (int r = 0; r < 16; ++r) ps += p1[r];
;     { auto rr = __builtin_amdgcn_permlane32_swap(__float_as_uint(ps), __float_as_uint(ps), false, false);
;       ps = __uint_as_float(rr[0]) + __uint_as_float(rr[1]); }
;     l_reg = l_reg * alpha + ps;
;     ...
;     PK4(p0, 0, pa0); PK4(p0, 8, pa1); PK4(p1, 0, pa2); PK4(p1, 8, pa3);
;     ...
; }
; __device__ __forceinline__ void qkt(f32x16& p0, f32x16& p1, const LAS char* Ks, const bf16x8* qr, const f32x16& negm, int r32, int hi) {
; #pragma unroll
;     for (int d0 = 0; d0 < 4; ++d0) { const int cb = (d0 * 16 + hi * 8) * 2;
;         const bf16x8 b0 = *(const LAS bf16x8*)(Ks + KSWZ(r32, cb));
;         const bf16x8 b1 = *(const LAS bf16x8*)(Ks + KSWZ(32 + r32, cb));
;         if (d0 == 0) { p0 = __builtin_amdgcn_mfma_f32_32x32x16_bf16(b0, qr[0], negm, 0, 0, 0); p1 = __builtin_amdgcn_mfma_f32_32x32x16_bf16(b1, qr[0], negm, 0, 0, 0); }
;         else { p0 = __builtin_amdgcn_mfma_f32_32x32x16_bf16(b0, qr[d0], p0, 0, 0, 0); p1 = __builtin_amdgcn_mfma_f32_32x32x16_bf16(b1, qr[d0], p1, 0, 0, 0); } }
; }
; __device__ __forceinline__ int v_st(int k, int c) { const int kk = (k & ~0xC) | ((k & 4) << 1) | ((k & 8) >> 1); return ((kk >> 3) * 4 + (c >> 5)) * 512 + ((kk & 7) * 32 + (c & 31)) * 2; }
; __device__ __forceinline__ int v_rd_base(int lane) { return ((lane & 3) << 3) | (((lane >> 2) & 3) << 6) | (((lane >> 4) & 1) << 5) | (((lane >> 5) & 1) << 8); }
; template <int OFF> __device__ __forceinline__ s16x4 tr_read(int vb) {
;     s16x4 r; asm volatile("ds_read_b64_tr_b16 %0, %1 offset:%2" : "=&v"(r) : "v"(vb), "i"(OFF) : "memory"); return r;
; }
; template <int D0> __device__ __forceinline__ void pv_one(f32x16& od, int vb, bf16x8 pa0, bf16x8 pa1, bf16x8 pa2, bf16x8 pa3) {
;     const s16x4 l0 = tr_read<v_rd_off(D0, 0, 0)>(vb), h0 = tr_read<v_rd_off(D0, 0, 1)>(vb), l1 = tr_read<v_rd_off(D0, 1, 0)>(vb), h1 = tr_read<v_rd_off(D0, 1, 1)>(vb);
	v_mov_b32_e32 v191, v190
	s_nop 1
	v_permlane32_swap_b32_e32 v190, v191
	v_cvt_pk_bf16_f32 v2, v2, v3
	v_cvt_pk_bf16_f32 v3, v4, v5
	v_cvt_pk_bf16_f32 v4, v6, v7
	v_cvt_pk_bf16_f32 v5, v8, v9
	v_cvt_pk_bf16_f32 v6, v10, v11
	v_cvt_pk_bf16_f32 v7, v12, v13
	v_cvt_pk_bf16_f32 v8, v128, v129
	v_cvt_pk_bf16_f32 v9, v130, v131
	v_cvt_pk_bf16_f32 v10, v112, v113
	v_cvt_pk_bf16_f32 v11, v114, v115
	v_cvt_pk_bf16_f32 v12, v116, v117
	v_cvt_pk_bf16_f32 v13, v118, v119
	v_cvt_pk_bf16_f32 v184, v120, v121
	v_cvt_pk_bf16_f32 v185, v122, v123
	v_cvt_pk_bf16_f32 v186, v124, v125
	v_cvt_pk_bf16_f32 v187, v126, v127
	v_permlane32_swap_b32_e32 v2, v4
	v_permlane32_swap_b32_e32 v3, v5
	v_permlane32_swap_b32_e32 v6, v8
	v_permlane32_swap_b32_e32 v7, v9
	v_permlane32_swap_b32_e32 v10, v12
	v_permlane32_swap_b32_e32 v11, v13
	v_permlane32_swap_b32_e32 v184, v186
	v_permlane32_swap_b32_e32 v185, v187
	s_setprio 1
	s_and_b32 s4, s38, 0x6000
	v_add_u32_e32 v200, s4, v241
	v_add_u32_e32 v112, v200, v237
	ds_read_b128 v[192:195], v112 offset:4096
	ds_read_b128 v[112:115], v112
	v_add_u32_e32 v196, v200, v238
	s_waitcnt lgkmcnt(0)
	v_mfma_f32_32x32x16_bf16 v[128:143], v[112:115], v[156:159], v[80:95]
	v_mfma_f32_32x32x16_bf16 v[112:127], v[192:195], v[156:159], v[80:95]
	ds_read_b128 v[192:195], v196 offset:4096
	ds_read_b128 v[196:199], v196
	s_waitcnt lgkmcnt(1)
	v_mfma_f32_32x32x16_bf16 v[112:127], v[192:195], v[152:155], v[112:127]
	s_waitcnt lgkmcnt(0)
	v_mfma_f32_32x32x16_bf16 v[128:143], v[196:199], v[152:155], v[128:143]
	v_add_u32_e32 v196, v200, v239
	ds_read_b128 v[192:195], v196 offset:4096
	ds_read_b128 v[196:199], v196
	s_waitcnt lgkmcnt(1)
	v_mfma_f32_32x32x16_bf16 v[112:127], v[192:195], v[148:151], v[112:127]
	s_waitcnt lgkmcnt(0)
	v_mfma_f32_32x32x16_bf16 v[128:143], v[196:199], v[148:151], v[128:143]
	v_add_u32_e32 v196, v200, v240
	ds_read_b128 v[192:195], v196 offset:4096
	ds_read_b128 v[196:199], v196
	v_lshl_add_u32 v200, s61, 14, v242
	s_waitcnt lgkmcnt(1)
	v_mfma_f32_32x32x16_bf16 v[112:127], v[192:195], v[144:147], v[112:127]
	ds_read_b64_tr_b16 v[192:193], v200 offset:0
	ds_read_b64_tr_b16 v[194:195], v200 offset:0x800
	s_waitcnt lgkmcnt(0)
	v_mfma_f32_32x32x16_bf16 v[128:143], v[196:199], v[144:147], v[128:143]
	ds_read_b64_tr_b16 v[196:197], v200 offset:0x1000
	ds_read_b64_tr_b16 v[198:199], v200 offset:0x1800
	ds_read_b64_tr_b16 v[220:221], v200 offset:0x2000
	ds_read_b64_tr_b16 v[222:223], v200 offset:0x2800
	ds_read_b64_tr_b16 v[244:245], v200 offset:0x3000
	ds_read_b64_tr_b16 v[246:247], v200 offset:0x3800
	s_waitcnt lgkmcnt(6)
	v_mfma_f32_32x32x16_bf16 v[64:79], v[2:5], v[192:195], v[64:79]
	ds_read_b64_tr_b16 v[192:193], v200 offset:0x200
	ds_read_b64_tr_b16 v[194:195], v200 offset:0xa00
	s_waitcnt lgkmcnt(6)
	v_mfma_f32_32x32x16_bf16 v[64:79], v[6:9], v[196:199], v[64:79]
	ds_read_b64_tr_b16 v[196:197], v200 offset:0x1200
	ds_read_b64_tr_b16 v[198:199], v200 offset:0x1a00
	s_waitcnt lgkmcnt(6)
	v_mfma_f32_32x32x16_bf16 v[64:79], v[10:13], v[220:223], v[64:79]
	ds_read_b64_tr_b16 v[220:221], v200 offset:0x2200
	ds_read_b64_tr_b16 v[222:223], v200 offset:0x2a00
	s_waitcnt lgkmcnt(6)
	v_mfma_f32_32x32x16_bf16 v[64:79], v[184:187], v[244:247], v[64:79]
	ds_read_b64_tr_b16 v[244:245], v200 offset:0x3200
	ds_read_b64_tr_b16 v[246:247], v200 offset:0x3a00
	s_waitcnt lgkmcnt(6)
	v_mfma_f32_32x32x16_bf16 v[48:63], v[2:5], v[192:195], v[48:63]
	ds_read_b64_tr_b16 v[192:193], v200 offset:0x400
	ds_read_b64_tr_b16 v[194:195], v200 offset:0xc00
	s_waitcnt lgkmcnt(6)
	v_mfma_f32_32x32x16_bf16 v[48:63], v[6:9], v[196:199], v[48:63]
	ds_read_b64_tr_b16 v[196:197], v200 offset:0x1400
	ds_read_b64_tr_b16 v[198:199], v200 offset:0x1c00
	s_waitcnt lgkmcnt(6)
	v_mfma_f32_32x32x16_bf16 v[48:63], v[10:13], v[220:223], v[48:63]
	ds_read_b64_tr_b16 v[220:221], v200 offset:0x2400
	ds_read_b64_tr_b16 v[222:223], v200 offset:0x2c00
	s_waitcnt lgkmcnt(6)
	v_mfma_f32_32x32x16_bf16 v[48:63], v[184:187], v[244:247], v[48:63]
	ds_read_b64_tr_b16 v[244:245], v200 offset:0x3400
	ds_read_b64_tr_b16 v[246:247], v200 offset:0x3c00
	s_waitcnt lgkmcnt(6)
	v_mfma_f32_32x32x16_bf16 v[32:47], v[2:5], v[192:195], v[32:47]
	ds_read_b64_tr_b16 v[192:193], v200 offset:0x600
	ds_read_b64_tr_b16 v[194:195], v200 offset:0xe00
	s_waitcnt lgkmcnt(6)
	v_mfma_f32_32x32x16_bf16 v[32:47], v[6:9], v[196:199], v[32:47]
	ds_read_b64_tr_b16 v[196:197], v200 offset:0x1600
	ds_read_b64_tr_b16 v[198:199], v200 offset:0x1e00
	s_waitcnt lgkmcnt(6)
	v_mfma_f32_32x32x16_bf16 v[32:47], v[10:13], v[220:223], v[32:47]
	ds_read_b64_tr_b16 v[220:221], v200 offset:0x2600
	ds_read_b64_tr_b16 v[222:223], v200 offset:0x2e00
	s_waitcnt lgkmcnt(6)
	v_mfma_f32_32x32x16_bf16 v[32:47], v[184:187], v[244:247], v[32:47]
	ds_read_b64_tr_b16 v[244:245], v200 offset:0x3600
	ds_read_b64_tr_b16 v[246:247], v200 offset:0x3e00
	s_waitcnt lgkmcnt(6)
	v_mfma_f32_32x32x16_bf16 v[16:31], v[2:5], v[192:195], v[16:31]
	s_waitcnt lgkmcnt(4)
	v_mfma_f32_32x32x16_bf16 v[16:31], v[6:9], v[196:199], v[16:31]
	s_waitcnt lgkmcnt(2)
	v_mfma_f32_32x32x16_bf16 v[16:31], v[10:13], v[220:223], v[16:31]
	s_waitcnt lgkmcnt(0)
	v_mfma_f32_32x32x16_bf16 v[16:31], v[184:187], v[244:247], v[16:31]
	s_setprio 0
	s_waitcnt lgkmcnt(0)
	s_barrier
	s_andn2_b64 vcc, exec, s[2:3]
	s_cbranch_vccnz .LBB0_600
	s_and_b32 s2, s49, 3
	s_lshl_b32 s3, s2, 14
	s_add_i32 s3, s3, 0
	v_add_u32_e32 v2, s3, v233
	v_add_u32_e32 v3, s3, v234
	v_lshl_add_u32 v4, s2, 13, v235
	s_waitcnt vmcnt(2)
	ds_write_b128 v2, v[160:163]
	s_waitcnt vmcnt(1)
	ds_write_b128 v3, v[164:167]
	s_waitcnt vmcnt(0)
	ds_write_b128 v4, v[168:171]

; #define LAS __attribute__((address_space(3)))
; #define SBAR() __builtin_amdgcn_sched_barrier(0)
; __device__ __forceinline__ void qkt(f32x16& p0, f32x16& p1, const LAS char* Ks, const bf16x8* qr, const f32x16& negm, int r32, int hi) {
; #pragma unroll
;     for (int d0 = 0; d0 < 4; ++d0) { const int cb = (d0 * 16 + hi * 8) * 2;
;         const bf16x8 b0 = *(const LAS bf16x8*)(Ks + KSWZ(r32, cb));
;         const bf16x8 b1 = *(const LAS bf16x8*)(Ks + KSWZ(32 + r32, cb));
;         if (d0 == 0) { p0 = __builtin_amdgcn_mfma_f32_32x32x16_bf16(b0, qr[0], negm, 0, 0, 0); p1 = __builtin_amdgcn_mfma_f32_32x32x16_bf16(b1, qr[0], negm, 0, 0, 0); }
;         else { p0 = __builtin_amdgcn_mfma_f32_32x32x16_bf16(b0, qr[d0], p0, 0, 0, 0); p1 = __builtin_amdgcn_mfma_f32_32x32x16_bf16(b1, qr[d0], p1, 0, 0, 0); } }
; }
; __device__ __forceinline__ int v_st(int k, int c) { const int kk = (k & ~0xC) | ((k & 4) << 1) | ((k & 8) >> 1); return ((kk >> 3) * 4 + (c >> 5)) * 512 + ((kk & 7) * 32 + (c & 31)) * 2; }
; __device__ __forceinline__ int v_rd_base(int lane) { return ((lane & 3) << 3) | (((lane >> 2) & 3) << 6) | (((lane >> 4) & 1) << 5) | (((lane >> 5) & 1) << 8); }
; template <int OFF> __device__ __forceinline__ s16x4 tr_read(int vb) {
;     s16x4 r; asm volatile("ds_read_b64_tr_b16 %0, %1 offset:%2" : "=&v"(r) : "v"(vb), "i"(OFF) : "memory"); return r;
; }
; template <int D0> __device__ __forceinline__ void pv_one(f32x16& od, int vb, bf16x8 pa0, bf16x8 pa1, bf16x8 pa2, bf16x8 pa3) {
;     const s16x4 l0 = tr_read<v_rd_off(D0, 0, 0)>(vb), h0 = tr_read<v_rd_off(D0, 0, 1)>(vb), l1 = tr_read<v_rd_off(D0, 1, 0)>(vb), h1 = tr_read<v_rd_off(D0, 1, 1)>(vb);
;     const s16x4 l2 = tr_read<v_rd_off(D0, 2, 0)>(vb), h2 = tr_read<v_rd_off(D0, 2, 1)>(vb), l3 = tr_read<v_rd_off(D0, 3, 0)>(vb), h3 = tr_read<v_rd_off(D0, 3, 1)>(vb);
;     asm volatile("s_waitcnt lgkmcnt(0)" ::: "memory"); SBAR();
;     ...
;     od = __builtin_amdgcn_mfma_f32_32x32x16_bf16(pa0, PK(l0, h0), od, 0, 0, 0);
;     od = __builtin_amdgcn_mfma_f32_32x32x16_bf16(pa1, PK(l1, h1), od, 0, 0, 0);
;     od = __builtin_amdgcn_mfma_f32_32x32x16_bf16(pa2, PK(l2, h2), od, 0, 0, 0);
;     od = __builtin_amdgcn_mfma_f32_32x32x16_bf16(pa3, PK(l3, h3), od, 0, 0, 0);
;     ...
; }
; __device__ __forceinline__ void pv_d0(f32x16* o, int vb, bf16x8 pa0, bf16x8 pa1, bf16x8 pa2, bf16x8 pa3) {
.LBB0_622:
	s_add_i32 s2, s34, -4
	s_setprio 1
	s_and_b32 s38, s2, 3
	v_lshl_add_u32 v0, s38, 13, v241
	v_add_u32_e32 v6, v0, v240
	ds_read_b128 v[2:5], v6 offset:4096
	ds_read_b128 v[6:9], v6
	s_and_b32 s2, s19, 0xc000
	s_waitcnt lgkmcnt(1)
	v_mfma_f32_32x32x16_bf16 v[112:127], v[2:5], v[156:159], v[96:111]
	s_waitcnt lgkmcnt(0)
	v_mfma_f32_32x32x16_bf16 v[128:143], v[6:9], v[156:159], v[96:111]
	v_add_u32_e32 v6, v0, v239
	ds_read_b128 v[2:5], v6 offset:4096
	ds_read_b128 v[6:9], v6
	s_waitcnt lgkmcnt(1)
	v_mfma_f32_32x32x16_bf16 v[112:127], v[2:5], v[152:155], v[112:127]
	s_waitcnt lgkmcnt(0)
	v_mfma_f32_32x32x16_bf16 v[128:143], v[6:9], v[152:155], v[128:143]
	v_add_u32_e32 v6, v0, v236
	ds_read_b128 v[2:5], v6 offset:4096
	ds_read_b128 v[6:9], v6
	v_add_u32_e32 v0, v0, v237
	s_waitcnt lgkmcnt(1)
	v_mfma_f32_32x32x16_bf16 v[112:127], v[2:5], v[148:151], v[112:127]
	s_waitcnt lgkmcnt(0)
	v_mfma_f32_32x32x16_bf16 v[128:143], v[6:9], v[148:151], v[128:143]
	ds_read_b128 v[2:5], v0 offset:4096
	ds_read_b128 v[6:9], v0
	v_add_u32_e32 v0, s2, v242
	s_waitcnt lgkmcnt(1)
	v_mfma_f32_32x32x16_bf16 v[112:127], v[2:5], v[144:147], v[112:127]
	ds_read_b64_tr_b16 v[2:3], v0 offset:0
	ds_read_b64_tr_b16 v[4:5], v0 offset:0x800
	s_waitcnt lgkmcnt(0)
	v_mfma_f32_32x32x16_bf16 v[128:143], v[6:9], v[144:147], v[128:143]
	ds_read_b64_tr_b16 v[6:7], v0 offset:0x1000
	ds_read_b64_tr_b16 v[8:9], v0 offset:0x1800
	ds_read_b64_tr_b16 v[10:11], v0 offset:0x2000
	ds_read_b64_tr_b16 v[12:13], v0 offset:0x2800
	ds_read_b64_tr_b16 v[80:81], v0 offset:0x3000
	ds_read_b64_tr_b16 v[82:83], v0 offset:0x3800
	s_waitcnt lgkmcnt(6)
	v_mfma_f32_32x32x16_bf16 v[64:79], v[184:187], v[2:5], v[64:79]
	ds_read_b64_tr_b16 v[2:3], v0 offset:0x200
	ds_read_b64_tr_b16 v[4:5], v0 offset:0xa00
	s_waitcnt lgkmcnt(6)
	v_mfma_f32_32x32x16_bf16 v[64:79], v[188:191], v[6:9], v[64:79]
	ds_read_b64_tr_b16 v[6:7], v0 offset:0x1200
	ds_read_b64_tr_b16 v[8:9], v0 offset:0x1a00
	s_waitcnt lgkmcnt(6)
	v_mfma_f32_32x32x16_bf16 v[64:79], v[192:195], v[10:13], v[64:79]
	ds_read_b64_tr_b16 v[10:11], v0 offset:0x2200
	ds_read_b64_tr_b16 v[12:13], v0 offset:0x2a00
	s_waitcnt lgkmcnt(6)
	v_mfma_f32_32x32x16_bf16 v[64:79], v[196:199], v[80:83], v[64:79]
	ds_read_b64_tr_b16 v[80:81], v0 offset:0x3200
	ds_read_b64_tr_b16 v[82:83], v0 offset:0x3a00
	s_waitcnt lgkmcnt(6)
	v_mfma_f32_32x32x16_bf16 v[48:63], v[184:187], v[2:5], v[48:63]
	ds_read_b64_tr_b16 v[2:3], v0 offset:0x400
	ds_read_b64_tr_b16 v[4:5], v0 offset:0xc00
	s_waitcnt lgkmcnt(6)
	v_mfma_f32_32x32x16_bf16 v[48:63], v[188:191], v[6:9], v[48:63]
	ds_read_b64_tr_b16 v[6:7], v0 offset:0x1400
	ds_read_b64_tr_b16 v[8:9], v0 offset:0x1c00
	s_waitcnt lgkmcnt(6)
	v_mfma_f32_32x32x16_bf16 v[48:63], v[192:195], v[10:13], v[48:63]
	ds_read_b64_tr_b16 v[10:11], v0 offset:0x2400
	ds_read_b64_tr_b16 v[12:13], v0 offset:0x2c00
	s_waitcnt lgkmcnt(6)
	v_mfma_f32_32x32x16_bf16 v[48:63], v[196:199], v[80:83], v[48:63]
	ds_read_b64_tr_b16 v[80:81], v0 offset:0x3400
	ds_read_b64_tr_b16 v[82:83], v0 offset:0x3c00
	s_waitcnt lgkmcnt(6)
	v_mfma_f32_32x32x16_bf16 v[32:47], v[184:187], v[2:5], v[32:47]
	ds_read_b64_tr_b16 v[2:3], v0 offset:0x600
	ds_read_b64_tr_b16 v[4:5], v0 offset:0xe00
	s_waitcnt lgkmcnt(6)
	v_mfma_f32_32x32x16_bf16 v[32:47], v[188:191], v[6:9], v[32:47]
	ds_read_b64_tr_b16 v[6:7], v0 offset:0x1600
	ds_read_b64_tr_b16 v[8:9], v0 offset:0x1e00
	s_waitcnt lgkmcnt(6)
	v_mfma_f32_32x32x16_bf16 v[32:47], v[192:195], v[10:13], v[32:47]
	ds_read_b64_tr_b16 v[10:11], v0 offset:0x2600
	ds_read_b64_tr_b16 v[12:13], v0 offset:0x2e00
	s_waitcnt lgkmcnt(6)
	v_mfma_f32_32x32x16_bf16 v[32:47], v[196:199], v[80:83], v[32:47]
	ds_read_b64_tr_b16 v[80:81], v0 offset:0x3600
	ds_read_b64_tr_b16 v[82:83], v0 offset:0x3e00
	s_waitcnt lgkmcnt(6)
	v_mfma_f32_32x32x16_bf16 v[16:31], v[184:187], v[2:5], v[16:31]
	s_waitcnt lgkmcnt(4)
	v_mfma_f32_32x32x16_bf16 v[16:31], v[188:191], v[6:9], v[16:31]
	s_waitcnt lgkmcnt(2)
	v_mfma_f32_32x32x16_bf16 v[16:31], v[192:195], v[10:13], v[16:31]
	s_waitcnt lgkmcnt(0)
	v_mfma_f32_32x32x16_bf16 v[16:31], v[196:199], v[80:83], v[16:31]
	s_setprio 0
	s_add_i32 s2, s34, -2
	s_and_b32 s2, s2, 3
	s_lshl_b32 s3, s2, 14
	s_add_i32 s3, s3, 0
	s_waitcnt lgkmcnt(0)
	s_barrier
	v_add_u32_e32 v0, s3, v233
	s_add_i32 s35, s34, -1
	s_waitcnt vmcnt(2)
	ds_write_b128 v0, v[172:175]
	v_add_u32_e32 v0, s3, v234
	s_cmp_lt_u32 s35, s45
	s_waitcnt vmcnt(1)
	ds_write_b128 v0, v[176:179]
	v_lshl_add_u32 v0, s2, 13, v235
	s_cselect_b64 s[2:3], -1, 0
	s_cmp_ge_u32 s35, s45
	v_lshl_add_u64 v[188:189], v[218:219], 0, s[36:37]
	v_lshl_add_u64 v[14:15], v[216:217], 0, s[36:37]
	s_waitcnt vmcnt(0)
	ds_write_b128 v0, v[180:183]
	s_cbranch_scc1 .LBB0_624
	v_add_co_u32_e32 v2, vcc, 0xef40000, v188
	s_nop 1
	v_addc_co_u32_e32 v3, vcc, 0, v189, vcc
	v_add_co_u32_e32 v4, vcc, 0xef48000, v188
	s_nop 1
	v_addc_co_u32_e32 v5, vcc, 0, v189, vcc
	global_load_dwordx4 v[160:163], v[2:3], off
	global_load_dwordx4 v[164:167], v[4:5], off
	v_add_co_u32_e32 v2, vcc, 0xcf40000, v14
	s_nop 1
	v_addc_co_u32_e32 v3, vcc, 0, v15, vcc
	global_load_dwordx4 v[168:171], v[2:3], off offset:128

; __device__ __forceinline__ void partialSM(f32x16& p0, f32x16& p1, float& mhat, f32x16& negm, float& alpha, const bool first) {
;     ...
;     for (int r = 0; r < 16; ++r) p0[r] = __builtin_amdgcn_exp2f(p0[r]);
; }
; __device__ __forceinline__ void finishSM(f32x16& p0, f32x16& p1, float alpha, float& l_reg, bf16x8& pa0, bf16x8& pa1, bf16x8& pa2, bf16x8& pa3) {
; #pragma unroll
;     for (int r = 0; r < 16; ++r) p1[r] = __builtin_amdgcn_exp2f(p1[r]);
;     float ps = 0;
; #pragma unroll
;     for (int r = 0; r < 16; ++r) ps += p0[r];
; #pragma unroll
;     for (int r = 0; r < 16; ++r) ps += p1[r];
;     { auto rr = __builtin_amdgcn_permlane32_swap(__float_as_uint(ps), __float_as_uint(ps), false, false);
;       ps = __uint_as_float(rr[0]) + __uint_as_float(rr[1]); }
;     l_reg = l_reg * alpha + ps;
.LBB0_629:
	v_exp_f32_e32 v2, v128
	v_exp_f32_e32 v3, v129
	v_exp_f32_e32 v4, v130
	v_exp_f32_e32 v5, v131
	v_exp_f32_e32 v6, v132
	v_add_f32_e32 v132, 0, v2
	v_exp_f32_e32 v7, v133
	v_add_f32_e32 v132, v3, v132
	v_exp_f32_e32 v8, v134
	v_add_f32_e32 v132, v4, v132
	v_exp_f32_e32 v9, v135
	v_add_f32_e32 v132, v5, v132
	v_exp_f32_e32 v10, v136
	v_add_f32_e32 v132, v6, v132
	v_exp_f32_e32 v11, v137
	v_add_f32_e32 v132, v7, v132
	v_exp_f32_e32 v12, v138
	v_add_f32_e32 v132, v8, v132
	v_exp_f32_e32 v13, v139
	v_add_f32_e32 v132, v9, v132
	v_exp_f32_e32 v128, v140
	v_add_f32_e32 v132, v10, v132
	v_exp_f32_e32 v129, v141
	v_add_f32_e32 v132, v11, v132
	v_exp_f32_e32 v130, v142
	v_add_f32_e32 v132, v12, v132
	v_exp_f32_e32 v131, v143
	v_add_f32_e32 v132, v13, v132
	v_exp_f32_e32 v112, v112
	v_add_f32_e32 v132, v128, v132
	v_exp_f32_e32 v113, v113
	v_add_f32_e32 v132, v129, v132
	v_exp_f32_e32 v114, v114
	v_add_f32_e32 v132, v130, v132
	v_exp_f32_e32 v115, v115
	v_add_f32_e32 v132, v131, v132
	v_exp_f32_e32 v116, v116
	v_add_f32_e32 v132, v112, v132
	v_exp_f32_e32 v117, v117
	v_add_f32_e32 v132, v113, v132
	v_exp_f32_e32 v118, v118
	v_add_f32_e32 v132, v114, v132
	v_exp_f32_e32 v119, v119
	v_add_f32_e32 v132, v115, v132
	v_exp_f32_e32 v120, v120
	v_add_f32_e32 v132, v116, v132
	v_exp_f32_e32 v121, v121
	v_add_f32_e32 v132, v117, v132
	v_exp_f32_e32 v122, v122
	v_add_f32_e32 v132, v118, v132
	v_exp_f32_e32 v123, v123
	v_add_f32_e32 v132, v119, v132
	v_exp_f32_e32 v124, v124
	v_add_f32_e32 v132, v120, v132
	v_exp_f32_e32 v125, v125
	v_add_f32_e32 v132, v121, v132
	v_exp_f32_e32 v126, v126
	v_add_f32_e32 v132, v122, v132
	v_exp_f32_e32 v127, v127
	v_add_f32_e32 v132, v123, v132
	v_add_f32_e32 v132, v124, v132
	v_add_f32_e32 v132, v125, v132
	v_add_f32_e32 v132, v126, v132
	v_add_f32_e32 v190, v127, v132
	s_waitcnt lgkmcnt(0)
	s_barrier
; #define LAS __attribute__((address_space(3)))
; __device__ __forceinline__ void finishSM(f32x16& p0, f32x16& p1, float alpha, float& l_reg, bf16x8& pa0, bf16x8& pa1, bf16x8& pa2, bf16x8& pa3) {
; #pragma unroll
;     for (int r = 0; r < 16; ++r) p1[r] = __builtin_amdgcn_exp2f(p1[r]);
;     float ps = 0;
; #pragma unroll
;     for (int r = 0; r < 16; ++r) ps += p0[r];
; #pragma unroll
;     for (int r = 0; r < 16; ++r) ps += p1[r];
;     { auto rr = __builtin_amdgcn_permlane32_swap(__float_as_uint(ps), __float_as_uint(ps), false, false);
;       ps = __uint_as_float(rr[0]) + __uint_as_float(rr[1]); }
;     l_reg = l_reg * alpha + ps;
;     ...
;     PK4(p0, 0, pa0); PK4(p0, 8, pa1); PK4(p1, 0, pa2); PK4(p1, 8, pa3);
;     ...
; }
; __device__ __forceinline__ void qkt(f32x16& p0, f32x16& p1, const LAS char* Ks, const bf16x8* qr, const f32x16& negm, int r32, int hi) {
; #pragma unroll
;     for (int d0 = 0; d0 < 4; ++d0) { const int cb = (d0 * 16 + hi * 8) * 2;
;         const bf16x8 b0 = *(const LAS bf16x8*)(Ks + KSWZ(r32, cb));
;         const bf16x8 b1 = *(const LAS bf16x8*)(Ks + KSWZ(32 + r32, cb));
;         if (d0 == 0) { p0 = __builtin_amdgcn_mfma_f32_32x32x16_bf16(b0, qr[0], negm, 0, 0, 0); p1 = __builtin_amdgcn_mfma_f32_32x32x16_bf16(b1, qr[0], negm, 0, 0, 0); }
;         else { p0 = __builtin_amdgcn_mfma_f32_32x32x16_bf16(b0, qr[d0], p0, 0, 0, 0); p1 = __builtin_amdgcn_mfma_f32_32x32x16_bf16(b1, qr[d0], p1, 0, 0, 0); } }
; }
; __device__ __forceinline__ int v_st(int k, int c) { const int kk = (k & ~0xC) | ((k & 4) << 1) | ((k & 8) >> 1); return ((kk >> 3) * 4 + (c >> 5)) * 512 + ((kk & 7) * 32 + (c & 31)) * 2; }
; __device__ __forceinline__ int v_rd_base(int lane) { return ((lane & 3) << 3) | (((lane >> 2) & 3) << 6) | (((lane >> 4) & 1) << 5) | (((lane >> 5) & 1) << 8); }
; template <int OFF> __device__ __forceinline__ s16x4 tr_read(int vb) {
;     s16x4 r; asm volatile("ds_read_b64_tr_b16 %0, %1 offset:%2" : "=&v"(r) : "v"(vb), "i"(OFF) : "memory"); return r;
; }
; template <int D0> __device__ __forceinline__ void pv_one(f32x16& od, int vb, bf16x8 pa0, bf16x8 pa1, bf16x8 pa2, bf16x8 pa3) {
;     const s16x4 l0 = tr_read<v_rd_off(D0, 0, 0)>(vb), h0 = tr_read<v_rd_off(D0, 0, 1)>(vb), l1 = tr_read<v_rd_off(D0, 1, 0)>(vb), h1 = tr_read<v_rd_off(D0, 1, 1)>(vb);
	v_mov_b32_e32 v191, v190
	s_nop 1
	v_permlane32_swap_b32_e32 v190, v191
	v_cvt_pk_bf16_f32 v2, v2, v3
	v_cvt_pk_bf16_f32 v3, v4, v5
	v_cvt_pk_bf16_f32 v4, v6, v7
	v_cvt_pk_bf16_f32 v5, v8, v9
	v_cvt_pk_bf16_f32 v6, v10, v11
	v_cvt_pk_bf16_f32 v7, v12, v13
	v_cvt_pk_bf16_f32 v8, v128, v129
	v_cvt_pk_bf16_f32 v9, v130, v131
	v_cvt_pk_bf16_f32 v10, v112, v113
	v_cvt_pk_bf16_f32 v11, v114, v115
	v_cvt_pk_bf16_f32 v12, v116, v117
	v_cvt_pk_bf16_f32 v13, v118, v119
	v_cvt_pk_bf16_f32 v184, v120, v121
	v_cvt_pk_bf16_f32 v185, v122, v123
	v_cvt_pk_bf16_f32 v186, v124, v125
	v_cvt_pk_bf16_f32 v187, v126, v127
	v_permlane32_swap_b32_e32 v2, v4
	v_permlane32_swap_b32_e32 v3, v5
	v_permlane32_swap_b32_e32 v6, v8
	v_permlane32_swap_b32_e32 v7, v9
	v_permlane32_swap_b32_e32 v10, v12
	v_permlane32_swap_b32_e32 v11, v13
	v_permlane32_swap_b32_e32 v184, v186
	v_permlane32_swap_b32_e32 v185, v187
	s_setprio 1
	s_and_b32 s4, s18, 0x6000
	v_add_u32_e32 v200, s4, v241
	v_add_u32_e32 v112, v200, v240
	ds_read_b128 v[192:195], v112 offset:4096
	ds_read_b128 v[112:115], v112
	v_add_u32_e32 v196, v200, v239
	s_waitcnt lgkmcnt(0)
	v_mfma_f32_32x32x16_bf16 v[128:143], v[112:115], v[156:159], v[80:95]
	v_mfma_f32_32x32x16_bf16 v[112:127], v[192:195], v[156:159], v[80:95]
	ds_read_b128 v[192:195], v196 offset:4096
	ds_read_b128 v[196:199], v196
	s_waitcnt lgkmcnt(1)
	v_mfma_f32_32x32x16_bf16 v[112:127], v[192:195], v[152:155], v[112:127]
	s_waitcnt lgkmcnt(0)
	v_mfma_f32_32x32x16_bf16 v[128:143], v[196:199], v[152:155], v[128:143]
	v_add_u32_e32 v196, v200, v236
	ds_read_b128 v[192:195], v196 offset:4096
	ds_read_b128 v[196:199], v196
	s_waitcnt lgkmcnt(1)
	v_mfma_f32_32x32x16_bf16 v[112:127], v[192:195], v[148:151], v[112:127]
	s_waitcnt lgkmcnt(0)
	v_mfma_f32_32x32x16_bf16 v[128:143], v[196:199], v[148:151], v[128:143]
	v_add_u32_e32 v196, v200, v237
	ds_read_b128 v[192:195], v196 offset:4096
	ds_read_b128 v[196:199], v196
	v_lshl_add_u32 v200, s38, 14, v242
	s_waitcnt lgkmcnt(1)
	v_mfma_f32_32x32x16_bf16 v[112:127], v[192:195], v[144:147], v[112:127]
	ds_read_b64_tr_b16 v[192:193], v200 offset:0
	ds_read_b64_tr_b16 v[194:195], v200 offset:0x800
	s_waitcnt lgkmcnt(0)
	v_mfma_f32_32x32x16_bf16 v[128:143], v[196:199], v[144:147], v[128:143]
	ds_read_b64_tr_b16 v[196:197], v200 offset:0x1000
	ds_read_b64_tr_b16 v[198:199], v200 offset:0x1800
	ds_read_b64_tr_b16 v[220:221], v200 offset:0x2000
	ds_read_b64_tr_b16 v[222:223], v200 offset:0x2800
	ds_read_b64_tr_b16 v[244:245], v200 offset:0x3000
	ds_read_b64_tr_b16 v[246:247], v200 offset:0x3800
	s_waitcnt lgkmcnt(6)
	v_mfma_f32_32x32x16_bf16 v[64:79], v[2:5], v[192:195], v[64:79]
	ds_read_b64_tr_b16 v[192:193], v200 offset:0x200
	ds_read_b64_tr_b16 v[194:195], v200 offset:0xa00
	s_waitcnt lgkmcnt(6)
	v_mfma_f32_32x32x16_bf16 v[64:79], v[6:9], v[196:199], v[64:79]
	ds_read_b64_tr_b16 v[196:197], v200 offset:0x1200
	ds_read_b64_tr_b16 v[198:199], v200 offset:0x1a00
	s_waitcnt lgkmcnt(6)
	v_mfma_f32_32x32x16_bf16 v[64:79], v[10:13], v[220:223], v[64:79]
	ds_read_b64_tr_b16 v[220:221], v200 offset:0x2200
	ds_read_b64_tr_b16 v[222:223], v200 offset:0x2a00
	s_waitcnt lgkmcnt(6)
	v_mfma_f32_32x32x16_bf16 v[64:79], v[184:187], v[244:247], v[64:79]
	ds_read_b64_tr_b16 v[244:245], v200 offset:0x3200
	ds_read_b64_tr_b16 v[246:247], v200 offset:0x3a00
	s_waitcnt lgkmcnt(6)
	v_mfma_f32_32x32x16_bf16 v[48:63], v[2:5], v[192:195], v[48:63]
	ds_read_b64_tr_b16 v[192:193], v200 offset:0x400
	ds_read_b64_tr_b16 v[194:195], v200 offset:0xc00
	s_waitcnt lgkmcnt(6)
	v_mfma_f32_32x32x16_bf16 v[48:63], v[6:9], v[196:199], v[48:63]
	ds_read_b64_tr_b16 v[196:197], v200 offset:0x1400
	ds_read_b64_tr_b16 v[198:199], v200 offset:0x1c00
	s_waitcnt lgkmcnt(6)
	v_mfma_f32_32x32x16_bf16 v[48:63], v[10:13], v[220:223], v[48:63]
	ds_read_b64_tr_b16 v[220:221], v200 offset:0x2400
	ds_read_b64_tr_b16 v[222:223], v200 offset:0x2c00
	s_waitcnt lgkmcnt(6)
	v_mfma_f32_32x32x16_bf16 v[48:63], v[184:187], v[244:247], v[48:63]
	ds_read_b64_tr_b16 v[244:245], v200 offset:0x3400
	ds_read_b64_tr_b16 v[246:247], v200 offset:0x3c00
	s_waitcnt lgkmcnt(6)
	v_mfma_f32_32x32x16_bf16 v[32:47], v[2:5], v[192:195], v[32:47]
	ds_read_b64_tr_b16 v[192:193], v200 offset:0x600
	ds_read_b64_tr_b16 v[194:195], v200 offset:0xe00
	s_waitcnt lgkmcnt(6)
	v_mfma_f32_32x32x16_bf16 v[32:47], v[6:9], v[196:199], v[32:47]
	ds_read_b64_tr_b16 v[196:197], v200 offset:0x1600
	ds_read_b64_tr_b16 v[198:199], v200 offset:0x1e00
	s_waitcnt lgkmcnt(6)
	v_mfma_f32_32x32x16_bf16 v[32:47], v[10:13], v[220:223], v[32:47]
	ds_read_b64_tr_b16 v[220:221], v200 offset:0x2600
	ds_read_b64_tr_b16 v[222:223], v200 offset:0x2e00
	s_waitcnt lgkmcnt(6)
	v_mfma_f32_32x32x16_bf16 v[32:47], v[184:187], v[244:247], v[32:47]
	ds_read_b64_tr_b16 v[244:245], v200 offset:0x3600
	ds_read_b64_tr_b16 v[246:247], v200 offset:0x3e00
	s_waitcnt lgkmcnt(6)
	v_mfma_f32_32x32x16_bf16 v[16:31], v[2:5], v[192:195], v[16:31]
	s_waitcnt lgkmcnt(4)
	v_mfma_f32_32x32x16_bf16 v[16:31], v[6:9], v[196:199], v[16:31]
	s_waitcnt lgkmcnt(2)
	v_mfma_f32_32x32x16_bf16 v[16:31], v[10:13], v[220:223], v[16:31]
	s_waitcnt lgkmcnt(0)
	v_mfma_f32_32x32x16_bf16 v[16:31], v[184:187], v[244:247], v[16:31]
	s_setprio 0
	s_waitcnt lgkmcnt(0)
	s_barrier
	s_andn2_b64 vcc, exec, s[2:3]
	s_cbranch_vccnz .LBB0_631
	s_and_b32 s2, s35, 3
	s_lshl_b32 s3, s2, 14
	s_add_i32 s3, s3, 0
	v_add_u32_e32 v2, s3, v233
	v_add_u32_e32 v3, s3, v234
	v_lshl_add_u32 v4, s2, 13, v235
	s_waitcnt vmcnt(2)
	ds_write_b128 v2, v[160:163]
	s_waitcnt vmcnt(1)
	ds_write_b128 v3, v[164:167]
	s_waitcnt vmcnt(0)
	ds_write_b128 v4, v[168:171]
